# v32 + LN1 router: group logits accumulated with plain v_fmac from the LN outputs and the resident w_group registers (64 FMAs) instead of packed ops fed by 64 gather moves; 61 VALU ops fewer per token
# speedup vs baseline: 1.0094x; 1.0059x over previous
.LBB0_552:
	s_add_i32 s23, s7, 1
	s_waitcnt vmcnt(0)
	v_mov_b64_e32 v[38:39], v[84:85]
	v_mov_b64_e32 v[32:33], v[92:93]
	v_mov_b64_e32 v[34:35], v[90:91]
	v_mov_b64_e32 v[36:37], v[88:89]
	v_mov_b32_e32 v0, s23
	v_min_u32_e32 v0, 15, v0
	v_mov_b32_e32 v1, 0
	v_lshl_add_u64 v[0:1], v[82:83], 0, v[0:1]
	v_lshlrev_b64 v[2:3], 12, v[0:1]
	v_lshlrev_b64 v[0:1], 11, v[0:1]
	v_lshl_add_u64 v[12:13], v[62:63], 0, v[2:3]
	v_lshl_add_u64 v[92:93], v[64:65], 0, v[0:1]
	global_load_dwordx4 v[0:3], v[12:13], off nt
	global_load_dwordx2 v[84:85], v[92:93], off nt
	global_load_dwordx4 v[4:7], v[12:13], off offset:1024 nt
	global_load_dwordx2 v[88:89], v[92:93], off offset:512 nt
	global_load_dwordx4 v[8:11], v[12:13], off offset:2048 nt
	global_load_dwordx2 v[90:91], v[92:93], off offset:1024 nt
	s_nop 0
	global_load_dwordx4 v[12:15], v[12:13], off offset:3072 nt
	s_nop 0
	global_load_dwordx2 v[92:93], v[92:93], off offset:1536 nt
	v_lshlrev_b32_e32 v40, 16, v38
	v_and_b32_e32 v41, 0xffff0000, v38
	v_lshlrev_b32_e32 v38, 16, v39
	v_and_b32_e32 v39, 0xffff0000, v39
	v_lshlrev_b32_e32 v54, 16, v36
	v_and_b32_e32 v55, 0xffff0000, v36
	v_lshlrev_b32_e32 v94, 16, v37
	v_and_b32_e32 v95, 0xffff0000, v37
	v_lshlrev_b32_e32 v96, 16, v34
	v_and_b32_e32 v97, 0xffff0000, v34
	v_lshlrev_b32_e32 v100, 16, v35
	v_and_b32_e32 v101, 0xffff0000, v35
	v_lshlrev_b32_e32 v102, 16, v32
	v_and_b32_e32 v103, 0xffff0000, v32
	v_lshlrev_b32_e32 v104, 16, v33
	v_and_b32_e32 v105, 0xffff0000, v33
	v_pk_fma_f32 v[106:107], v[30:31], s[22:23], v[38:39] op_sel_hi:[1,0,1]
	ds_read_b128 v[30:33], v234
	ds_read_b128 v[34:37], v234 offset:4096
	v_pk_fma_f32 v[28:29], v[28:29], s[22:23], v[40:41] op_sel_hi:[1,0,1]
	v_pk_fma_f32 v[20:21], v[20:21], s[22:23], v[54:55] op_sel_hi:[1,0,1]
	v_add_f32_e32 v38, v28, v29
	v_add_f32_e32 v38, v38, v106
	v_pk_fma_f32 v[22:23], v[22:23], s[22:23], v[94:95] op_sel_hi:[1,0,1]
	v_add_f32_e32 v54, v20, v21
	v_pk_fma_f32 v[24:25], v[24:25], s[22:23], v[96:97] op_sel_hi:[1,0,1]
	v_add_f32_e32 v38, v107, v38
	v_add_f32_e32 v54, v54, v22
	v_pk_fma_f32 v[26:27], v[26:27], s[22:23], v[100:101] op_sel_hi:[1,0,1]
	v_add_f32_e32 v55, v24, v25
	v_add_f32_e32 v98, 0, v38
	v_add_f32_e32 v54, v23, v54
	v_add_f32_e32 v55, v55, v26
	v_add_f32_e32 v54, v98, v54
	v_add_f32_e32 v55, v27, v55
	v_pk_fma_f32 v[16:17], v[16:17], s[22:23], v[102:103] op_sel_hi:[1,0,1]
	v_add_f32_e32 v54, v54, v55
	v_pk_fma_f32 v[18:19], v[18:19], s[22:23], v[104:105] op_sel_hi:[1,0,1]
	v_add_f32_e32 v55, v16, v17
	v_add_f32_e32 v55, v55, v18
	v_add_f32_e32 v55, v19, v55
	v_add_f32_e32 v54, v54, v55
	ds_read_b128 v[38:41], v60
	ds_read_b128 v[42:45], v60 offset:4096
	ds_read_b128 v[46:49], v60 offset:8192
	ds_read_b128 v[50:53], v60 offset:12288
	ds_read_b128 v[108:111], v60 offset:16384
	ds_read_b128 v[122:125], v60 offset:20480
	ds_read_b128 v[130:133], v60 offset:24576
	ds_read_b128 v[134:137], v60 offset:28672
	ds_read_b128 v[138:141], v60 offset:32768
	ds_read_b128 v[142:145], v60 offset:36864
	ds_read_b128 v[146:149], v60 offset:40960
	ds_read_b128 v[150:153], v60 offset:45056
	ds_read_b128 v[154:157], v60 offset:49152
	v_add_f32_dpp v54, v54, v54 quad_perm:[1,0,3,2] row_mask:0xf bank_mask:0xf bound_ctrl:1
	s_nop 1
	v_add_f32_dpp v54, v54, v54 quad_perm:[2,3,0,1] row_mask:0xf bank_mask:0xf bound_ctrl:1
	s_nop 1
	v_add_f32_dpp v54, v54, v54 row_half_mirror row_mask:0xf bank_mask:0xf bound_ctrl:1
	s_nop 1
	v_add_f32_dpp v54, v54, v54 row_mirror row_mask:0xf bank_mask:0xf bound_ctrl:1
	s_nop 0
	v_readlane_b32 s2, v54, 16
	v_readlane_b32 s4, v54, 48
	v_readlane_b32 s0, v54, 0
	v_readlane_b32 s1, v54, 32
	v_mov_b32_e32 v54, s2
	v_mov_b32_e32 v55, s4
	v_pk_add_f32 v[54:55], s[0:1], v[54:55]
	s_nop 0
	v_add_f32_e32 v54, v54, v55
	v_mul_f32_e32 v54, 0x3a800000, v54
	v_pk_add_f32 v[28:29], v[28:29], v[54:55] op_sel_hi:[1,0] neg_lo:[0,1] neg_hi:[0,1]
	v_pk_add_f32 v[126:127], v[106:107], v[54:55] op_sel_hi:[1,0] neg_lo:[0,1] neg_hi:[0,1]
	v_pk_mul_f32 v[104:105], v[28:29], v[28:29]
	v_pk_mul_f32 v[106:107], v[126:127], v[126:127]
	v_pk_add_f32 v[158:159], v[20:21], v[54:55] op_sel_hi:[1,0] neg_lo:[0,1] neg_hi:[0,1]
	v_pk_add_f32 v[160:161], v[22:23], v[54:55] op_sel_hi:[1,0] neg_lo:[0,1] neg_hi:[0,1]
	v_pk_add_f32 v[100:101], v[24:25], v[54:55] op_sel_hi:[1,0] neg_lo:[0,1] neg_hi:[0,1]
	v_pk_add_f32 v[102:103], v[26:27], v[54:55] op_sel_hi:[1,0] neg_lo:[0,1] neg_hi:[0,1]
	v_pk_add_f32 v[94:95], v[16:17], v[54:55] op_sel_hi:[1,0] neg_lo:[0,1] neg_hi:[0,1]
	v_pk_add_f32 v[96:97], v[18:19], v[54:55] op_sel_hi:[1,0] neg_lo:[0,1] neg_hi:[0,1]
	v_add_f32_e32 v54, v104, v105
	v_add_f32_e32 v54, v106, v54
	v_pk_mul_f32 v[20:21], v[158:159], v[158:159]
	v_add_f32_e32 v54, v107, v54
	v_add_f32_e32 v20, v20, v54
	v_pk_mul_f32 v[22:23], v[160:161], v[160:161]
	v_add_f32_e32 v20, v21, v20
	v_add_f32_e32 v20, v22, v20
	v_pk_mul_f32 v[24:25], v[100:101], v[100:101]
	v_add_f32_e32 v20, v23, v20
	v_add_f32_e32 v20, v24, v20
	v_pk_mul_f32 v[26:27], v[102:103], v[102:103]
	v_add_f32_e32 v20, v25, v20
	v_add_f32_e32 v20, v26, v20
	v_pk_mul_f32 v[16:17], v[94:95], v[94:95]
	v_add_f32_e32 v20, v27, v20
	v_add_f32_e32 v16, v16, v20
	v_pk_mul_f32 v[18:19], v[96:97], v[96:97]
	v_add_f32_e32 v16, v17, v16
	v_add_f32_e32 v16, v18, v16
	v_add_f32_e32 v16, v19, v16
	s_nop 1
	v_add_f32_dpp v16, v16, v16 quad_perm:[1,0,3,2] row_mask:0xf bank_mask:0xf bound_ctrl:1
	s_nop 1
	v_add_f32_dpp v16, v16, v16 quad_perm:[2,3,0,1] row_mask:0xf bank_mask:0xf bound_ctrl:1
	s_nop 1
	v_add_f32_dpp v16, v16, v16 row_half_mirror row_mask:0xf bank_mask:0xf bound_ctrl:1
	s_nop 1
	v_add_f32_dpp v16, v16, v16 row_mirror row_mask:0xf bank_mask:0xf bound_ctrl:1
	s_nop 0
	v_readlane_b32 s2, v16, 16
	v_readlane_b32 s4, v16, 48
	v_readlane_b32 s0, v16, 0
	v_readlane_b32 s1, v16, 32
	v_mov_b32_e32 v16, s2
	v_mov_b32_e32 v17, s4
	v_pk_add_f32 v[16:17], s[0:1], v[16:17]
	s_mov_b32 s0, 0x800000
	v_add_f32_e32 v16, v16, v17
	v_fmamk_f32 v16, v16, 0x3a800000, v116
	v_cmp_gt_f32_e32 vcc, s0, v16
	v_mul_f32_e32 v17, 0x4b800000, v16
	s_nop 0
	v_cndmask_b32_e32 v16, v16, v17, vcc
	v_rsq_f32_e32 v54, v16
	ds_read_b128 v[16:19], v60 offset:53248
	s_waitcnt lgkmcnt(15)
	ds_read_b128 v[20:23], v60 offset:57344
	s_waitcnt lgkmcnt(15)
	ds_read_b128 v[24:27], v60 offset:61440
	s_waitcnt lgkmcnt(15)
	v_mul_f32_e32 v55, 0x45800000, v54
	v_cndmask_b32_e32 v98, v54, v55, vcc
	v_pk_mul_f32 v[28:29], v[28:29], v[98:99] op_sel_hi:[1,0]
	v_pk_fma_f32 v[106:107], v[30:31], v[28:29], v[34:35]
	v_pk_mul_f32 v[28:29], v[126:127], v[98:99] op_sel_hi:[1,0]
	s_waitcnt lgkmcnt(2)
	v_mul_f32_e32 v17, v107, v17
	v_pk_fma_f32 v[104:105], v[32:33], v[28:29], v[36:37]
	v_cvt_pk_bf16_f32 v28, v106, v107
	v_cvt_pk_bf16_f32 v29, v104, v105
	v_mul_f32_e32 v252, v106, v183
	v_mul_f32_e32 v253, v106, v184
	v_mul_f32_e32 v254, v106, v182
	v_mul_f32_e32 v255, v106, v185
	v_fmac_f32_e32 v252, v107, v187
	v_fmac_f32_e32 v253, v107, v188
	v_fmac_f32_e32 v254, v107, v186
	v_fmac_f32_e32 v255, v107, v189
	v_fmac_f32_e32 v252, v104, v191
	v_fmac_f32_e32 v253, v104, v192
	v_fmac_f32_e32 v254, v104, v190
	v_fmac_f32_e32 v255, v104, v193
	v_fmac_f32_e32 v252, v105, v195
	v_fmac_f32_e32 v253, v105, v196
	v_fmac_f32_e32 v254, v105, v194
	v_fmac_f32_e32 v255, v105, v197
	global_store_dwordx2 v[86:87], v[28:29], off offset:-1024
	v_mul_f32_e32 v54, v39, v107
	v_fmac_f32_e32 v54, v38, v106
	ds_read_b128 v[32:35], v234 offset:1024
	ds_read_b128 v[36:39], v234 offset:5120
	v_fmac_f32_e32 v54, v104, v40
	v_fmac_f32_e32 v54, v105, v41
	v_mul_f32_e32 v55, v107, v43
	v_fmac_f32_e32 v55, v106, v42
	v_fmac_f32_e32 v55, v104, v44
	v_fmac_f32_e32 v55, v105, v45
	v_mul_f32_e32 v28, v107, v47
	v_fmac_f32_e32 v28, v106, v46
	v_fmac_f32_e32 v28, v104, v48
	v_fmac_f32_e32 v28, v105, v49
	v_add_f32_e32 v46, 0, v28
	v_mul_f32_e32 v45, v107, v51
	v_fmac_f32_e32 v45, v106, v50
	v_fmac_f32_e32 v45, v104, v52
	v_fmac_f32_e32 v45, v105, v53
	v_mul_f32_e32 v44, v107, v109
	v_fmac_f32_e32 v44, v106, v108
	v_fmac_f32_e32 v44, v104, v110
	v_fmac_f32_e32 v44, v105, v111
	v_mul_f32_e32 v53, v107, v123
	v_fmac_f32_e32 v53, v106, v122
	v_fmac_f32_e32 v53, v104, v124
	v_fmac_f32_e32 v53, v105, v125
	v_mul_f32_e32 v52, v107, v131
	v_fmac_f32_e32 v52, v106, v130
	v_fmac_f32_e32 v52, v104, v132
	v_fmac_f32_e32 v52, v105, v133
	v_mul_f32_e32 v51, v107, v135
	v_fmac_f32_e32 v51, v106, v134
	v_fmac_f32_e32 v51, v104, v136
	v_fmac_f32_e32 v51, v105, v137
	v_mul_f32_e32 v50, v107, v139
	v_fmac_f32_e32 v50, v106, v138
	v_fmac_f32_e32 v50, v104, v140
	v_fmac_f32_e32 v50, v105, v141
	v_mul_f32_e32 v49, v107, v143
	v_fmac_f32_e32 v49, v106, v142
	v_fmac_f32_e32 v49, v104, v144
	v_fmac_f32_e32 v49, v105, v145
	v_mul_f32_e32 v48, v107, v147
	v_fmac_f32_e32 v48, v106, v146
	v_fmac_f32_e32 v48, v104, v148
	v_fmac_f32_e32 v48, v105, v149
	v_mul_f32_e32 v131, v107, v151
	v_fmac_f32_e32 v17, v106, v16
	s_waitcnt lgkmcnt(3)
	v_mul_f32_e32 v122, v107, v21
	v_fmac_f32_e32 v131, v106, v150
	v_fmac_f32_e32 v122, v106, v20
	v_fmac_f32_e32 v131, v104, v152
	v_fmac_f32_e32 v122, v104, v22
	v_fmac_f32_e32 v131, v105, v153
	v_fmac_f32_e32 v122, v105, v23
	v_mul_f32_e32 v125, v107, v155
	s_waitcnt lgkmcnt(2)
	v_mul_f32_e32 v123, v107, v25
	v_fmac_f32_e32 v125, v106, v154
	v_fmac_f32_e32 v123, v106, v24
	v_fmac_f32_e32 v125, v104, v156
	v_fmac_f32_e32 v17, v104, v18
	v_fmac_f32_e32 v123, v104, v26
	v_fmac_f32_e32 v125, v105, v157
	v_fmac_f32_e32 v17, v105, v19
	v_fmac_f32_e32 v123, v105, v27
	v_pk_mul_f32 v[40:41], v[158:159], v[98:99] op_sel_hi:[1,0]
	v_add_f32_e32 v124, 0, v17
	s_waitcnt lgkmcnt(0)
	v_pk_fma_f32 v[108:109], v[40:41], v[32:33], v[36:37]
	ds_read_b128 v[40:43], v60 offset:1024
	ds_read_b128 v[134:137], v60 offset:21504
	v_pk_mul_f32 v[32:33], v[160:161], v[98:99] op_sel_hi:[1,0]
	ds_read_b128 v[142:145], v60 offset:29696
	v_pk_fma_f32 v[110:111], v[32:33], v[34:35], v[38:39]
	s_waitcnt lgkmcnt(2)
	v_fma_f32 v126, v109, v41, v54
	v_cvt_pk_bf16_f32 v32, v108, v109
	v_cvt_pk_bf16_f32 v33, v110, v111
	v_fmac_f32_e32 v252, v108, v199
	v_fmac_f32_e32 v253, v108, v200
	v_fmac_f32_e32 v254, v108, v198
	v_fmac_f32_e32 v255, v108, v201
	v_fmac_f32_e32 v252, v109, v203
	v_fmac_f32_e32 v253, v109, v204
	v_fmac_f32_e32 v254, v109, v202
	v_fmac_f32_e32 v255, v109, v205
	v_fmac_f32_e32 v252, v110, v207
	v_fmac_f32_e32 v253, v110, v208
	v_fmac_f32_e32 v254, v110, v206
	v_fmac_f32_e32 v255, v110, v209
	v_fmac_f32_e32 v252, v111, v211
	v_fmac_f32_e32 v253, v111, v212
	v_fmac_f32_e32 v254, v111, v210
	v_fmac_f32_e32 v255, v111, v213
	v_fmac_f32_e32 v126, v108, v40
	global_store_dwordx2 v[86:87], v[32:33], off offset:-512
	ds_read_b128 v[32:35], v60 offset:5120
	v_fmac_f32_e32 v126, v110, v42
	v_fmac_f32_e32 v126, v111, v43
	s_waitcnt lgkmcnt(2)
	v_fma_f32 v133, v109, v135, v53
	s_waitcnt lgkmcnt(1)
	v_fma_f32 v135, v109, v143, v51
	v_fmac_f32_e32 v135, v108, v142
	v_fmac_f32_e32 v135, v110, v144
	v_fmac_f32_e32 v135, v111, v145
	ds_read_b128 v[144:147], v60 offset:50176
	s_waitcnt lgkmcnt(1)
	v_fma_f32 v127, v109, v33, v55
	v_fmac_f32_e32 v127, v108, v32
	v_fmac_f32_e32 v127, v110, v34
	v_fmac_f32_e32 v127, v111, v35
	ds_read_b128 v[36:39], v60 offset:9216
	ds_read_b128 v[32:35], v60 offset:13312
	ds_read_b128 v[40:43], v60 offset:17408
	ds_read_b128 v[138:141], v60 offset:25600
	v_fmac_f32_e32 v133, v108, v134
	v_fmac_f32_e32 v133, v110, v136
	s_waitcnt lgkmcnt(3)
	v_fma_f32 v129, v109, v37, v46
	s_waitcnt lgkmcnt(2)
	v_fma_f32 v130, v109, v33, v45
	v_fmac_f32_e32 v133, v111, v137
	v_fmac_f32_e32 v129, v108, v36
	v_fmac_f32_e32 v130, v108, v32
	s_waitcnt lgkmcnt(0)
	v_fma_f32 v134, v109, v139, v52
	v_fmac_f32_e32 v129, v110, v38
	v_fmac_f32_e32 v130, v110, v34
	v_fma_f32 v132, v109, v41, v44
	v_fmac_f32_e32 v134, v108, v138
	v_fmac_f32_e32 v129, v111, v39
	v_fmac_f32_e32 v130, v111, v35
	v_fmac_f32_e32 v132, v108, v40
	v_fmac_f32_e32 v134, v110, v140
	v_fmac_f32_e32 v132, v110, v42
	v_fmac_f32_e32 v134, v111, v141
	v_fmac_f32_e32 v132, v111, v43
	ds_read_b128 v[52:55], v60 offset:33792
	ds_read_b128 v[138:141], v60 offset:37888
	s_waitcnt lgkmcnt(1)
	v_fma_f32 v136, v109, v53, v50
	v_fmac_f32_e32 v136, v108, v52
	v_fmac_f32_e32 v136, v110, v54
	v_fmac_f32_e32 v136, v111, v55
	ds_read_b128 v[50:53], v60 offset:41984
	s_waitcnt lgkmcnt(1)
	v_fma_f32 v137, v109, v139, v49
	v_fmac_f32_e32 v137, v108, v138
	v_fmac_f32_e32 v137, v110, v140
	v_fmac_f32_e32 v137, v111, v141
	ds_read_b128 v[140:143], v60 offset:46080
	s_waitcnt lgkmcnt(1)
	v_fma_f32 v138, v109, v51, v48
	v_fmac_f32_e32 v138, v108, v50
	v_fmac_f32_e32 v138, v110, v52
	v_fmac_f32_e32 v138, v111, v53
	ds_read_b128 v[48:51], v234 offset:2048
	ds_read_b128 v[52:55], v234 offset:6144
	s_waitcnt lgkmcnt(2)
	v_fma_f32 v131, v109, v141, v131
	v_fmac_f32_e32 v131, v108, v140
	v_fmac_f32_e32 v131, v110, v142
	v_fmac_f32_e32 v131, v111, v143
	ds_read_b128 v[140:143], v60 offset:54272
	v_fma_f32 v139, v109, v145, v125
	v_fmac_f32_e32 v139, v108, v144
	v_fmac_f32_e32 v139, v110, v146
	v_fmac_f32_e32 v139, v111, v147
	ds_read_b128 v[144:147], v60 offset:58368
	s_waitcnt lgkmcnt(1)
	v_fma_f32 v148, v109, v141, v124
	v_fmac_f32_e32 v148, v108, v140
	v_fmac_f32_e32 v148, v110, v142
	v_fmac_f32_e32 v148, v111, v143
	ds_read_b128 v[140:143], v60 offset:62464
	s_waitcnt lgkmcnt(1)
	v_mul_f32_e32 v124, v109, v145
	v_fmac_f32_e32 v124, v108, v144
	v_fmac_f32_e32 v124, v110, v146
	v_fmac_f32_e32 v124, v111, v147
	v_add_f32_e32 v144, v122, v124
	s_waitcnt lgkmcnt(0)
	v_mul_f32_e32 v122, v109, v141
	v_fmac_f32_e32 v122, v108, v140
	v_fmac_f32_e32 v122, v110, v142
	v_fmac_f32_e32 v122, v111, v143
	v_add_f32_e32 v142, v123, v122
	v_pk_mul_f32 v[20:21], v[102:103], v[98:99] op_sel_hi:[1,0]
	v_pk_fma_f32 v[50:51], v[20:21], v[50:51], v[54:55]
	v_pk_mul_f32 v[16:17], v[100:101], v[98:99] op_sel_hi:[1,0]
	v_cvt_pk_bf16_f32 v21, v50, v51
	v_pk_fma_f32 v[48:49], v[16:17], v[48:49], v[52:53]
	ds_read_b128 v[16:19], v60 offset:2048
	v_cvt_pk_bf16_f32 v20, v48, v49
	v_fmac_f32_e32 v252, v50, v223
	v_fmac_f32_e32 v253, v50, v224
	v_fmac_f32_e32 v254, v50, v222
	v_fmac_f32_e32 v255, v50, v225
	v_fmac_f32_e32 v252, v51, v227
	v_fmac_f32_e32 v253, v51, v228
	v_fmac_f32_e32 v254, v51, v226
	v_fmac_f32_e32 v255, v51, v229
	v_fmac_f32_e32 v252, v48, v215
	v_fmac_f32_e32 v253, v48, v216
	v_fmac_f32_e32 v254, v48, v214
	v_fmac_f32_e32 v255, v48, v217
	v_fmac_f32_e32 v252, v49, v219
	v_fmac_f32_e32 v253, v49, v220
	v_fmac_f32_e32 v254, v49, v218
	v_fmac_f32_e32 v255, v49, v221
	global_store_dwordx2 v[86:87], v[20:21], off
	ds_read_b128 v[20:23], v60 offset:6144
	v_pk_mul_f32 v[46:47], v[94:95], v[98:99] op_sel_hi:[1,0]
	s_waitcnt lgkmcnt(1)
	v_fma_f32 v42, v49, v17, v126
	v_fmac_f32_e32 v42, v48, v16
	v_fmac_f32_e32 v42, v50, v18
	v_fmac_f32_e32 v42, v51, v19
	ds_read_b128 v[16:19], v60 offset:10240
	s_waitcnt lgkmcnt(1)
	v_fma_f32 v41, v49, v21, v127
	v_fmac_f32_e32 v41, v48, v20
	v_fmac_f32_e32 v41, v50, v22
	v_fmac_f32_e32 v41, v51, v23
	ds_read_b128 v[20:23], v60 offset:14336
	s_waitcnt lgkmcnt(1)
	v_fma_f32 v40, v49, v17, v129
	v_fmac_f32_e32 v40, v48, v16
	v_fmac_f32_e32 v40, v50, v18
	v_fmac_f32_e32 v40, v51, v19
	ds_read_b128 v[16:19], v60 offset:18432
	ds_read_b128 v[32:35], v234 offset:3072
	ds_read_b128 v[36:39], v234 offset:7168
	s_waitcnt lgkmcnt(3)
	v_fma_f32 v45, v49, v21, v130
	v_fmac_f32_e32 v45, v48, v20
	v_fmac_f32_e32 v45, v50, v22
	v_fmac_f32_e32 v45, v51, v23
	ds_read_b128 v[20:23], v60 offset:22528
	s_waitcnt lgkmcnt(3)
	v_fma_f32 v44, v49, v17, v132
	v_fmac_f32_e32 v44, v48, v16
	v_fmac_f32_e32 v44, v50, v18
	v_fmac_f32_e32 v44, v51, v19
	ds_read_b128 v[16:19], v60 offset:26624
	s_waitcnt lgkmcnt(1)
	v_fma_f32 v124, v49, v21, v133
	v_fmac_f32_e32 v124, v48, v20
	v_fmac_f32_e32 v124, v50, v22
	v_fmac_f32_e32 v124, v51, v23
	ds_read_b128 v[20:23], v60 offset:30720
	s_waitcnt lgkmcnt(1)
	v_fma_f32 v123, v49, v17, v134
	v_fmac_f32_e32 v123, v48, v16
	v_fmac_f32_e32 v123, v50, v18
	v_fmac_f32_e32 v123, v51, v19
	s_waitcnt lgkmcnt(0)
	v_fma_f32 v122, v49, v21, v135
	v_fmac_f32_e32 v122, v48, v20
	v_fmac_f32_e32 v122, v50, v22
	ds_read_b128 v[16:19], v60 offset:34816
	v_fmac_f32_e32 v122, v51, v23
	ds_read_b128 v[20:23], v60 offset:38912
	s_waitcnt lgkmcnt(1)
	v_fma_f32 v111, v49, v17, v136
	v_fmac_f32_e32 v111, v48, v16
	v_fmac_f32_e32 v111, v50, v18
	s_waitcnt lgkmcnt(0)
	v_fma_f32 v110, v49, v21, v137
	v_fmac_f32_e32 v110, v48, v20
	v_fmac_f32_e32 v111, v51, v19
	v_fmac_f32_e32 v110, v50, v22
	ds_read_b128 v[16:19], v60 offset:43008
	v_fmac_f32_e32 v110, v51, v23
	ds_read_b128 v[20:23], v60 offset:47104
	s_waitcnt lgkmcnt(1)
	v_fma_f32 v109, v49, v17, v138
	v_fmac_f32_e32 v109, v48, v16
	v_fmac_f32_e32 v109, v50, v18
	s_waitcnt lgkmcnt(0)
	v_fma_f32 v108, v49, v21, v131
	v_fmac_f32_e32 v108, v48, v20
	v_fmac_f32_e32 v109, v51, v19
	v_fmac_f32_e32 v108, v50, v22
	ds_read_b128 v[16:19], v60 offset:51200
	v_fmac_f32_e32 v108, v51, v23
	ds_read_b128 v[20:23], v60 offset:55296
	s_waitcnt lgkmcnt(1)
	v_fma_f32 v103, v49, v17, v139
	v_fmac_f32_e32 v103, v48, v16
	v_fmac_f32_e32 v103, v50, v18
	s_waitcnt lgkmcnt(0)
	v_fma_f32 v102, v49, v21, v148
	v_fmac_f32_e32 v102, v48, v20
	v_fmac_f32_e32 v103, v51, v19
	v_fmac_f32_e32 v102, v50, v22
	ds_read_b128 v[16:19], v60 offset:59392
	v_fmac_f32_e32 v102, v51, v23
	ds_read_b128 v[20:23], v60 offset:63488
	s_waitcnt lgkmcnt(1)
	v_fma_f32 v100, v49, v17, v144
	v_fmac_f32_e32 v100, v48, v16
	v_fmac_f32_e32 v100, v50, v18
	s_waitcnt lgkmcnt(0)
	v_fma_f32 v101, v49, v21, v142
	v_fmac_f32_e32 v101, v48, v20
	v_fmac_f32_e32 v101, v50, v22
	v_fmac_f32_e32 v100, v51, v19
	v_fmac_f32_e32 v101, v51, v23
	v_pk_fma_f32 v[52:53], v[46:47], v[32:33], v[36:37]
	v_pk_mul_f32 v[32:33], v[96:97], v[98:99] op_sel_hi:[1,0]
	ds_read_b128 v[94:97], v60 offset:3072
	v_pk_fma_f32 v[54:55], v[32:33], v[34:35], v[38:39]
	v_cvt_pk_bf16_f32 v32, v52, v53
	v_cvt_pk_bf16_f32 v33, v54, v55
	v_fmac_f32_e32 v252, v52, v231
	v_fmac_f32_e32 v253, v52, v232
	v_fmac_f32_e32 v254, v52, v230
	v_fmac_f32_e32 v255, v52, v233
	v_fmac_f32_e32 v252, v53, v239
	v_fmac_f32_e32 v253, v53, v240
	v_fmac_f32_e32 v254, v53, v238
	v_fmac_f32_e32 v255, v53, v241
	v_fmac_f32_e32 v252, v54, v243
	v_fmac_f32_e32 v253, v54, v244
	v_fmac_f32_e32 v254, v54, v242
	v_fmac_f32_e32 v255, v54, v245
	v_fmac_f32_e32 v252, v55, v247
	v_fmac_f32_e32 v253, v55, v248
	v_fmac_f32_e32 v254, v55, v246
	v_fmac_f32_e32 v255, v55, v249
	global_store_dwordx2 v[86:87], v[32:33], off offset:512
	ds_read_b128 v[32:35], v60 offset:7168
	s_waitcnt lgkmcnt(1)
	v_mul_f32_e32 v36, v53, v95
	v_fmac_f32_e32 v36, v52, v94
	v_fmac_f32_e32 v36, v54, v96
	v_fmac_f32_e32 v36, v55, v97
	v_add_f32_e32 v94, v42, v36
	ds_read_b128 v[36:39], v60 offset:11264
	ds_read_b128 v[130:133], v60 offset:15360
	s_waitcnt lgkmcnt(2)
	v_fma_f32 v95, v53, v33, v41
	v_fmac_f32_e32 v95, v52, v32
	v_fmac_f32_e32 v95, v54, v34
	s_waitcnt lgkmcnt(1)
	v_fma_f32 v96, v53, v37, v40
	v_fmac_f32_e32 v96, v52, v36
	v_fmac_f32_e32 v96, v54, v38
	v_fmac_f32_e32 v95, v55, v35
	v_fmac_f32_e32 v96, v55, v39
	ds_read_b128 v[40:43], v60 offset:19456
	s_waitcnt lgkmcnt(1)
	v_fma_f32 v97, v53, v131, v45
	v_fmac_f32_e32 v97, v52, v130
	v_fmac_f32_e32 v97, v54, v132
	v_fmac_f32_e32 v97, v55, v133
	ds_read_b128 v[130:133], v60 offset:23552
	s_waitcnt lgkmcnt(1)
	v_fma_f32 v125, v53, v41, v44
	v_fmac_f32_e32 v125, v52, v40
	v_fmac_f32_e32 v125, v54, v42
	v_fmac_f32_e32 v125, v55, v43
	ds_read_b128 v[134:137], v60 offset:27648
	s_waitcnt lgkmcnt(1)
	v_fma_f32 v124, v53, v131, v124
	v_fmac_f32_e32 v124, v52, v130
	v_fmac_f32_e32 v124, v54, v132
	v_fmac_f32_e32 v124, v55, v133
	ds_read_b128 v[130:133], v60 offset:31744
	s_waitcnt lgkmcnt(1)
	v_fma_f32 v98, v53, v135, v123
	v_fmac_f32_e32 v98, v52, v134
	v_fmac_f32_e32 v98, v54, v136
	v_fmac_f32_e32 v98, v55, v137
	ds_read_b128 v[134:137], v60 offset:35840
	s_waitcnt lgkmcnt(1)
	v_fma_f32 v122, v53, v131, v122
	v_fmac_f32_e32 v122, v52, v130
	v_fmac_f32_e32 v122, v54, v132
	v_fmac_f32_e32 v122, v55, v133
	ds_read_b128 v[130:133], v60 offset:39936
	s_waitcnt lgkmcnt(1)
	v_fma_f32 v111, v53, v135, v111
	v_fmac_f32_e32 v111, v52, v134
	v_fmac_f32_e32 v111, v54, v136
	v_fmac_f32_e32 v111, v55, v137
	ds_read_b128 v[134:137], v60 offset:44032
	s_waitcnt lgkmcnt(1)
	v_fma_f32 v110, v53, v131, v110
	v_fmac_f32_e32 v110, v52, v130
	v_fmac_f32_e32 v110, v54, v132
	v_fmac_f32_e32 v110, v55, v133
	ds_read_b128 v[130:133], v60 offset:48128
	s_waitcnt lgkmcnt(1)
	v_fma_f32 v109, v53, v135, v109
	v_fmac_f32_e32 v109, v52, v134
	v_fmac_f32_e32 v109, v54, v136
	v_fmac_f32_e32 v109, v55, v137
	ds_read_b128 v[134:137], v60 offset:52224
	s_waitcnt lgkmcnt(1)
	v_fma_f32 v108, v53, v131, v108
	v_fmac_f32_e32 v108, v52, v130
	v_fmac_f32_e32 v108, v54, v132
	v_fmac_f32_e32 v108, v55, v133
	ds_read_b128 v[130:133], v60 offset:56320
	s_waitcnt lgkmcnt(1)
	v_fma_f32 v103, v53, v135, v103
	v_fmac_f32_e32 v103, v52, v134
	v_fmac_f32_e32 v103, v54, v136
	v_fmac_f32_e32 v103, v55, v137
	ds_read_b128 v[134:137], v60 offset:60416
	s_waitcnt lgkmcnt(1)
	v_fma_f32 v102, v53, v131, v102
	v_fmac_f32_e32 v102, v52, v130
	v_fmac_f32_e32 v102, v54, v132
	v_fmac_f32_e32 v102, v55, v133
	ds_read_b128 v[130:133], v60 offset:64512
	s_waitcnt lgkmcnt(1)
	v_fma_f32 v123, v53, v135, v100
	v_fmac_f32_e32 v123, v52, v134
	v_fmac_f32_e32 v123, v54, v136
	v_fmac_f32_e32 v123, v55, v137
	s_waitcnt lgkmcnt(0)
	v_fma_f32 v129, v53, v131, v101
	v_fmac_f32_e32 v129, v52, v130
	v_fmac_f32_e32 v129, v54, v132
	v_fmac_f32_e32 v129, v55, v133
	v_add_f32_dpp v250, v252, v252 row_mirror row_mask:0xf bank_mask:0xf bound_ctrl:1
	v_add_f32_dpp v250, v253, v253 row_mirror row_mask:0xf bank_mask:0xc bound_ctrl:1
	v_add_f32_dpp v251, v254, v254 row_mirror row_mask:0xf bank_mask:0xf bound_ctrl:1
	v_add_f32_dpp v251, v255, v255 row_mirror row_mask:0xf bank_mask:0xc bound_ctrl:1
	v_add_f32_dpp v250, v250, v250 row_half_mirror row_mask:0xf bank_mask:0xf bound_ctrl:1
	s_nop 0
	v_add_f32_dpp v250, v251, v251 row_half_mirror row_mask:0xf bank_mask:0xa bound_ctrl:1
	s_nop 1
	v_add_f32_dpp v250, v250, v250 quad_perm:[1,0,3,2] row_mask:0xf bank_mask:0xf bound_ctrl:1
	s_nop 1
	v_add_f32_dpp v250, v250, v250 quad_perm:[2,3,0,1] row_mask:0xf bank_mask:0xf bound_ctrl:1
	s_nop 0
	v_readlane_b32 s2, v250, 20
	v_readlane_b32 s4, v250, 52
	v_readlane_b32 s0, v250, 4
	v_readlane_b32 s1, v250, 36
	v_mov_b32_e32 v16, s2
	v_mov_b32_e32 v17, s4
	v_readlane_b32 s2, v250, 16
	v_readlane_b32 s4, v250, 48
	v_pk_add_f32 v[16:17], s[0:1], v[16:17]
	v_readlane_b32 s0, v250, 0
	v_readlane_b32 s1, v250, 32
	v_mov_b32_e32 v18, s2
	v_mov_b32_e32 v19, s4
	v_readlane_b32 s2, v250, 24
	v_readlane_b32 s4, v250, 56
	v_pk_add_f32 v[18:19], s[0:1], v[18:19]
	v_readlane_b32 s0, v250, 8
	v_readlane_b32 s1, v250, 40
	v_mov_b32_e32 v20, s2
	v_mov_b32_e32 v21, s4
	v_pk_add_f32 v[20:21], s[0:1], v[20:21]
	v_mov_b32_e32 v25, v18
	v_add_f32_e32 v26, v20, v21
	v_mov_b32_e32 v18, v17
	v_readlane_b32 s2, v250, 28
	v_readlane_b32 s4, v250, 60
	v_readlane_b32 s0, v250, 12
	v_readlane_b32 s1, v250, 44
	v_mov_b32_e32 v20, s2
	v_mov_b32_e32 v21, s4
	v_pk_add_f32 v[20:21], s[0:1], v[20:21]
	v_add_f32_e32 v27, v20, v21
	v_mov_b32_e32 v24, v16
	v_pk_add_f32 v[16:17], v[24:25], v[18:19]
	v_mov_b32_e32 v20, v178
	v_mov_b32_e32 v21, v179
	v_mov_b32_e32 v22, v180
	v_mov_b32_e32 v23, v181
	v_add_f32_e32 v19, v26, v22
	v_pk_add_f32 v[16:17], v[16:17], v[20:21]
	v_add_f32_e32 v18, v27, v23
	v_cmp_gt_f32_e32 vcc, v17, v16
	s_nop 0
	s_nop 0
	v_cndmask_b32_e32 v20, v16, v17, vcc
	v_cmp_gt_f32_e64 s[18:19], v19, v20
	v_cndmask_b32_e64 v21, 0, 1, vcc
	s_and_b64 s[14:15], s[18:19], exec
	v_cndmask_b32_e64 v20, v20, v19, s[18:19]
	v_cmp_ngt_f32_e64 s[0:1], v18, v20
	v_readfirstlane_b32 s2, v21
	s_cselect_b32 s2, 2, s2
	s_and_b64 s[14:15], s[0:1], exec
	s_cselect_b32 s2, s2, 3
	s_cmp_eq_u32 s2, 0
	s_cbranch_scc0 .Lmy_rsela_1
	v_add_f32_dpp v94, v94, v94 row_mirror row_mask:0xf bank_mask:0xf bound_ctrl:1
	v_add_f32_dpp v94, v95, v95 row_mirror row_mask:0xf bank_mask:0xc bound_ctrl:1
	v_add_f32_dpp v96, v96, v96 row_mirror row_mask:0xf bank_mask:0xf bound_ctrl:1
	v_add_f32_dpp v96, v97, v97 row_mirror row_mask:0xf bank_mask:0xc bound_ctrl:1
	v_add_f32_dpp v94, v94, v94 row_half_mirror row_mask:0xf bank_mask:0xf bound_ctrl:1
	s_nop 0
	v_add_f32_dpp v94, v96, v96 row_half_mirror row_mask:0xf bank_mask:0xa bound_ctrl:1
	s_nop 1
	v_add_f32_dpp v94, v94, v94 quad_perm:[1,0,3,2] row_mask:0xf bank_mask:0xf bound_ctrl:1
	s_nop 1
	v_add_f32_dpp v94, v94, v94 quad_perm:[2,3,0,1] row_mask:0xf bank_mask:0xf bound_ctrl:1
	s_nop 0
	v_readlane_b32 s20, v94, 0
	v_readlane_b32 s4, v94, 16
	v_readlane_b32 s21, v94, 32
	v_readlane_b32 s5, v94, 48
	v_readlane_b32 s91, v94, 8
	v_readlane_b32 s95, v94, 24
	v_readlane_b32 s94, v94, 40
	v_readlane_b32 s92, v94, 56
	v_readlane_b32 s6, v94, 4
	v_readlane_b32 s75, v94, 20
	v_readlane_b32 s74, v94, 36
	v_readlane_b32 s84, v94, 52
	v_readlane_b32 s97, v94, 12
	v_readlane_b32 s9, v94, 28
	v_readlane_b32 s8, v94, 44
	v_readlane_b32 s12, v94, 60
	s_branch .Lmy_rsela_end

.LBB0_1676:
	s_add_i32 s21, s19, 1
	s_waitcnt vmcnt(0)
	v_mov_b64_e32 v[38:39], v[84:85]
	v_mov_b64_e32 v[32:33], v[92:93]
	v_mov_b64_e32 v[34:35], v[90:91]
	v_mov_b64_e32 v[36:37], v[88:89]
	v_mov_b32_e32 v0, s21
	v_min_u32_e32 v0, 15, v0
	v_mov_b32_e32 v1, 0
	v_lshl_add_u64 v[0:1], v[82:83], 0, v[0:1]
	v_lshlrev_b64 v[2:3], 12, v[0:1]
	v_lshlrev_b64 v[0:1], 11, v[0:1]
	v_lshl_add_u64 v[12:13], v[62:63], 0, v[2:3]
	v_lshl_add_u64 v[92:93], v[64:65], 0, v[0:1]
	global_load_dwordx4 v[0:3], v[12:13], off nt
	global_load_dwordx2 v[84:85], v[92:93], off nt
	global_load_dwordx4 v[4:7], v[12:13], off offset:1024 nt
	global_load_dwordx2 v[88:89], v[92:93], off offset:512 nt
	global_load_dwordx4 v[8:11], v[12:13], off offset:2048 nt
	global_load_dwordx2 v[90:91], v[92:93], off offset:1024 nt
	s_nop 0
	global_load_dwordx4 v[12:15], v[12:13], off offset:3072 nt
	s_nop 0
	global_load_dwordx2 v[92:93], v[92:93], off offset:1536 nt
	v_lshlrev_b32_e32 v40, 16, v38
	v_and_b32_e32 v41, 0xffff0000, v38
	v_lshlrev_b32_e32 v38, 16, v39
	v_and_b32_e32 v39, 0xffff0000, v39
	v_lshlrev_b32_e32 v54, 16, v36
	v_and_b32_e32 v55, 0xffff0000, v36
	v_lshlrev_b32_e32 v94, 16, v37
	v_and_b32_e32 v95, 0xffff0000, v37
	v_lshlrev_b32_e32 v96, 16, v34
	v_and_b32_e32 v97, 0xffff0000, v34
	v_lshlrev_b32_e32 v100, 16, v35
	v_and_b32_e32 v101, 0xffff0000, v35
	v_lshlrev_b32_e32 v102, 16, v32
	v_and_b32_e32 v103, 0xffff0000, v32
	v_lshlrev_b32_e32 v104, 16, v33
	v_and_b32_e32 v105, 0xffff0000, v33
	v_pk_fma_f32 v[106:107], v[30:31], s[20:21], v[38:39] op_sel_hi:[1,0,1]
	ds_read_b128 v[30:33], v234
	ds_read_b128 v[34:37], v234 offset:4096
	v_pk_fma_f32 v[28:29], v[28:29], s[20:21], v[40:41] op_sel_hi:[1,0,1]
	v_pk_fma_f32 v[20:21], v[20:21], s[20:21], v[54:55] op_sel_hi:[1,0,1]
	v_add_f32_e32 v38, v28, v29
	v_add_f32_e32 v38, v38, v106
	v_pk_fma_f32 v[22:23], v[22:23], s[20:21], v[94:95] op_sel_hi:[1,0,1]
	v_add_f32_e32 v54, v20, v21
	v_pk_fma_f32 v[24:25], v[24:25], s[20:21], v[96:97] op_sel_hi:[1,0,1]
	v_add_f32_e32 v38, v107, v38
	v_add_f32_e32 v54, v54, v22
	v_pk_fma_f32 v[26:27], v[26:27], s[20:21], v[100:101] op_sel_hi:[1,0,1]
	v_add_f32_e32 v55, v24, v25
	v_add_f32_e32 v98, 0, v38
	v_add_f32_e32 v54, v23, v54
	v_add_f32_e32 v55, v55, v26
	v_add_f32_e32 v54, v98, v54
	v_add_f32_e32 v55, v27, v55
	v_pk_fma_f32 v[16:17], v[16:17], s[20:21], v[102:103] op_sel_hi:[1,0,1]
	v_add_f32_e32 v54, v54, v55
	v_pk_fma_f32 v[18:19], v[18:19], s[20:21], v[104:105] op_sel_hi:[1,0,1]
	v_add_f32_e32 v55, v16, v17
	v_add_f32_e32 v55, v55, v18
	v_add_f32_e32 v55, v19, v55
	v_add_f32_e32 v54, v54, v55
	ds_read_b128 v[38:41], v60
	ds_read_b128 v[42:45], v60 offset:4096
	ds_read_b128 v[46:49], v60 offset:8192
	ds_read_b128 v[50:53], v60 offset:12288
	ds_read_b128 v[108:111], v60 offset:16384
	ds_read_b128 v[122:125], v60 offset:20480
	ds_read_b128 v[130:133], v60 offset:24576
	ds_read_b128 v[134:137], v60 offset:28672
	ds_read_b128 v[138:141], v60 offset:32768
	ds_read_b128 v[142:145], v60 offset:36864
	ds_read_b128 v[146:149], v60 offset:40960
	ds_read_b128 v[150:153], v60 offset:45056
	ds_read_b128 v[154:157], v60 offset:49152
	v_add_f32_dpp v54, v54, v54 quad_perm:[1,0,3,2] row_mask:0xf bank_mask:0xf bound_ctrl:1
	s_nop 1
	v_add_f32_dpp v54, v54, v54 quad_perm:[2,3,0,1] row_mask:0xf bank_mask:0xf bound_ctrl:1
	s_nop 1
	v_add_f32_dpp v54, v54, v54 row_half_mirror row_mask:0xf bank_mask:0xf bound_ctrl:1
	s_nop 1
	v_add_f32_dpp v54, v54, v54 row_mirror row_mask:0xf bank_mask:0xf bound_ctrl:1
	s_nop 0
	v_readlane_b32 s2, v54, 16
	v_readlane_b32 s10, v54, 48
	v_readlane_b32 s0, v54, 0
	v_readlane_b32 s1, v54, 32
	v_mov_b32_e32 v54, s2
	v_mov_b32_e32 v55, s10
	v_pk_add_f32 v[54:55], s[0:1], v[54:55]
	s_nop 0
	v_add_f32_e32 v54, v54, v55
	v_mul_f32_e32 v54, 0x3a800000, v54
	v_pk_add_f32 v[28:29], v[28:29], v[54:55] op_sel_hi:[1,0] neg_lo:[0,1] neg_hi:[0,1]
	v_pk_add_f32 v[126:127], v[106:107], v[54:55] op_sel_hi:[1,0] neg_lo:[0,1] neg_hi:[0,1]
	v_pk_mul_f32 v[104:105], v[28:29], v[28:29]
	v_pk_mul_f32 v[106:107], v[126:127], v[126:127]
	v_pk_add_f32 v[158:159], v[20:21], v[54:55] op_sel_hi:[1,0] neg_lo:[0,1] neg_hi:[0,1]
	v_pk_add_f32 v[160:161], v[22:23], v[54:55] op_sel_hi:[1,0] neg_lo:[0,1] neg_hi:[0,1]
	v_pk_add_f32 v[100:101], v[24:25], v[54:55] op_sel_hi:[1,0] neg_lo:[0,1] neg_hi:[0,1]
	v_pk_add_f32 v[102:103], v[26:27], v[54:55] op_sel_hi:[1,0] neg_lo:[0,1] neg_hi:[0,1]
	v_pk_add_f32 v[94:95], v[16:17], v[54:55] op_sel_hi:[1,0] neg_lo:[0,1] neg_hi:[0,1]
	v_pk_add_f32 v[96:97], v[18:19], v[54:55] op_sel_hi:[1,0] neg_lo:[0,1] neg_hi:[0,1]
	v_add_f32_e32 v54, v104, v105
	v_add_f32_e32 v54, v106, v54
	v_pk_mul_f32 v[20:21], v[158:159], v[158:159]
	v_add_f32_e32 v54, v107, v54
	v_add_f32_e32 v20, v20, v54
	v_pk_mul_f32 v[22:23], v[160:161], v[160:161]
	v_add_f32_e32 v20, v21, v20
	v_add_f32_e32 v20, v22, v20
	v_pk_mul_f32 v[24:25], v[100:101], v[100:101]
	v_add_f32_e32 v20, v23, v20
	v_add_f32_e32 v20, v24, v20
	v_pk_mul_f32 v[26:27], v[102:103], v[102:103]
	v_add_f32_e32 v20, v25, v20
	v_add_f32_e32 v20, v26, v20
	v_pk_mul_f32 v[16:17], v[94:95], v[94:95]
	v_add_f32_e32 v20, v27, v20
	v_add_f32_e32 v16, v16, v20
	v_pk_mul_f32 v[18:19], v[96:97], v[96:97]
	v_add_f32_e32 v16, v17, v16
	v_add_f32_e32 v16, v18, v16
	v_add_f32_e32 v16, v19, v16
	s_nop 1
	v_add_f32_dpp v16, v16, v16 quad_perm:[1,0,3,2] row_mask:0xf bank_mask:0xf bound_ctrl:1
	s_nop 1
	v_add_f32_dpp v16, v16, v16 quad_perm:[2,3,0,1] row_mask:0xf bank_mask:0xf bound_ctrl:1
	s_nop 1
	v_add_f32_dpp v16, v16, v16 row_half_mirror row_mask:0xf bank_mask:0xf bound_ctrl:1
	s_nop 1
	v_add_f32_dpp v16, v16, v16 row_mirror row_mask:0xf bank_mask:0xf bound_ctrl:1
	s_nop 0
	v_readlane_b32 s2, v16, 16
	v_readlane_b32 s10, v16, 48
	v_readlane_b32 s0, v16, 0
	v_readlane_b32 s1, v16, 32
	v_mov_b32_e32 v16, s2
	v_mov_b32_e32 v17, s10
	v_pk_add_f32 v[16:17], s[0:1], v[16:17]
	s_mov_b32 s0, 0x800000
	v_add_f32_e32 v16, v16, v17
	v_fmamk_f32 v16, v16, 0x3a800000, v116
	v_cmp_gt_f32_e32 vcc, s0, v16
	v_mul_f32_e32 v17, 0x4b800000, v16
	s_nop 0
	v_cndmask_b32_e32 v16, v16, v17, vcc
	v_rsq_f32_e32 v54, v16
	ds_read_b128 v[16:19], v60 offset:53248
	s_waitcnt lgkmcnt(15)
	ds_read_b128 v[20:23], v60 offset:57344
	s_waitcnt lgkmcnt(15)
	ds_read_b128 v[24:27], v60 offset:61440
	s_waitcnt lgkmcnt(15)
	v_mul_f32_e32 v55, 0x45800000, v54
	v_cndmask_b32_e32 v98, v54, v55, vcc
	v_pk_mul_f32 v[28:29], v[28:29], v[98:99] op_sel_hi:[1,0]
	v_pk_fma_f32 v[106:107], v[30:31], v[28:29], v[34:35]
	v_pk_mul_f32 v[28:29], v[126:127], v[98:99] op_sel_hi:[1,0]
	s_waitcnt lgkmcnt(2)
	v_mul_f32_e32 v17, v107, v17
	v_pk_fma_f32 v[104:105], v[32:33], v[28:29], v[36:37]
	v_cvt_pk_bf16_f32 v28, v106, v107
	v_cvt_pk_bf16_f32 v29, v104, v105
	v_mul_f32_e32 v252, v106, v183
	v_mul_f32_e32 v253, v106, v184
	v_mul_f32_e32 v254, v106, v182
	v_mul_f32_e32 v255, v106, v185
	v_fmac_f32_e32 v252, v107, v187
	v_fmac_f32_e32 v253, v107, v188
	v_fmac_f32_e32 v254, v107, v186
	v_fmac_f32_e32 v255, v107, v189
	v_fmac_f32_e32 v252, v104, v191
	v_fmac_f32_e32 v253, v104, v192
	v_fmac_f32_e32 v254, v104, v190
	v_fmac_f32_e32 v255, v104, v193
	v_fmac_f32_e32 v252, v105, v195
	v_fmac_f32_e32 v253, v105, v196
	v_fmac_f32_e32 v254, v105, v194
	v_fmac_f32_e32 v255, v105, v197
	global_store_dwordx2 v[86:87], v[28:29], off offset:-1024
	v_mul_f32_e32 v54, v39, v107
	v_fmac_f32_e32 v54, v38, v106
	ds_read_b128 v[32:35], v234 offset:1024
	ds_read_b128 v[36:39], v234 offset:5120
	v_fmac_f32_e32 v54, v104, v40
	v_fmac_f32_e32 v54, v105, v41
	v_mul_f32_e32 v55, v107, v43
	v_fmac_f32_e32 v55, v106, v42
	v_fmac_f32_e32 v55, v104, v44
	v_fmac_f32_e32 v55, v105, v45
	v_mul_f32_e32 v28, v107, v47
	v_fmac_f32_e32 v28, v106, v46
	v_fmac_f32_e32 v28, v104, v48
	v_fmac_f32_e32 v28, v105, v49
	v_add_f32_e32 v46, 0, v28
	v_mul_f32_e32 v45, v107, v51
	v_fmac_f32_e32 v45, v106, v50
	v_fmac_f32_e32 v45, v104, v52
	v_fmac_f32_e32 v45, v105, v53
	v_mul_f32_e32 v44, v107, v109
	v_fmac_f32_e32 v44, v106, v108
	v_fmac_f32_e32 v44, v104, v110
	v_fmac_f32_e32 v44, v105, v111
	v_mul_f32_e32 v53, v107, v123
	v_fmac_f32_e32 v53, v106, v122
	v_fmac_f32_e32 v53, v104, v124
	v_fmac_f32_e32 v53, v105, v125
	v_mul_f32_e32 v52, v107, v131
	v_fmac_f32_e32 v52, v106, v130
	v_fmac_f32_e32 v52, v104, v132
	v_fmac_f32_e32 v52, v105, v133
	v_mul_f32_e32 v51, v107, v135
	v_fmac_f32_e32 v51, v106, v134
	v_fmac_f32_e32 v51, v104, v136
	v_fmac_f32_e32 v51, v105, v137
	v_mul_f32_e32 v50, v107, v139
	v_fmac_f32_e32 v50, v106, v138
	v_fmac_f32_e32 v50, v104, v140
	v_fmac_f32_e32 v50, v105, v141
	v_mul_f32_e32 v49, v107, v143
	v_fmac_f32_e32 v49, v106, v142
	v_fmac_f32_e32 v49, v104, v144
	v_fmac_f32_e32 v49, v105, v145
	v_mul_f32_e32 v48, v107, v147
	v_fmac_f32_e32 v48, v106, v146
	v_fmac_f32_e32 v48, v104, v148
	v_fmac_f32_e32 v48, v105, v149
	v_mul_f32_e32 v131, v107, v151
	v_fmac_f32_e32 v17, v106, v16
	s_waitcnt lgkmcnt(3)
	v_mul_f32_e32 v122, v107, v21
	v_fmac_f32_e32 v131, v106, v150
	v_fmac_f32_e32 v122, v106, v20
	v_fmac_f32_e32 v131, v104, v152
	v_fmac_f32_e32 v122, v104, v22
	v_fmac_f32_e32 v131, v105, v153
	v_fmac_f32_e32 v122, v105, v23
	v_mul_f32_e32 v125, v107, v155
	s_waitcnt lgkmcnt(2)
	v_mul_f32_e32 v123, v107, v25
	v_fmac_f32_e32 v125, v106, v154
	v_fmac_f32_e32 v123, v106, v24
	v_fmac_f32_e32 v125, v104, v156
	v_fmac_f32_e32 v17, v104, v18
	v_fmac_f32_e32 v123, v104, v26
	v_fmac_f32_e32 v125, v105, v157
	v_fmac_f32_e32 v17, v105, v19
	v_fmac_f32_e32 v123, v105, v27
	v_pk_mul_f32 v[40:41], v[158:159], v[98:99] op_sel_hi:[1,0]
	v_add_f32_e32 v124, 0, v17
	s_waitcnt lgkmcnt(0)
	v_pk_fma_f32 v[108:109], v[40:41], v[32:33], v[36:37]
	ds_read_b128 v[40:43], v60 offset:1024
	ds_read_b128 v[134:137], v60 offset:21504
	v_pk_mul_f32 v[32:33], v[160:161], v[98:99] op_sel_hi:[1,0]
	ds_read_b128 v[142:145], v60 offset:29696
	v_pk_fma_f32 v[110:111], v[32:33], v[34:35], v[38:39]
	s_waitcnt lgkmcnt(2)
	v_fma_f32 v126, v109, v41, v54
	v_cvt_pk_bf16_f32 v32, v108, v109
	v_cvt_pk_bf16_f32 v33, v110, v111
	v_fmac_f32_e32 v252, v108, v199
	v_fmac_f32_e32 v253, v108, v200
	v_fmac_f32_e32 v254, v108, v198
	v_fmac_f32_e32 v255, v108, v201
	v_fmac_f32_e32 v252, v109, v203
	v_fmac_f32_e32 v253, v109, v204
	v_fmac_f32_e32 v254, v109, v202
	v_fmac_f32_e32 v255, v109, v205
	v_fmac_f32_e32 v252, v110, v207
	v_fmac_f32_e32 v253, v110, v208
	v_fmac_f32_e32 v254, v110, v206
	v_fmac_f32_e32 v255, v110, v209
	v_fmac_f32_e32 v252, v111, v211
	v_fmac_f32_e32 v253, v111, v212
	v_fmac_f32_e32 v254, v111, v210
	v_fmac_f32_e32 v255, v111, v213
	v_fmac_f32_e32 v126, v108, v40
	global_store_dwordx2 v[86:87], v[32:33], off offset:-512
	ds_read_b128 v[32:35], v60 offset:5120
	v_fmac_f32_e32 v126, v110, v42
	v_fmac_f32_e32 v126, v111, v43
	s_waitcnt lgkmcnt(2)
	v_fma_f32 v133, v109, v135, v53
	s_waitcnt lgkmcnt(1)
	v_fma_f32 v135, v109, v143, v51
	v_fmac_f32_e32 v135, v108, v142
	v_fmac_f32_e32 v135, v110, v144
	v_fmac_f32_e32 v135, v111, v145
	ds_read_b128 v[144:147], v60 offset:50176
	s_waitcnt lgkmcnt(1)
	v_fma_f32 v127, v109, v33, v55
	v_fmac_f32_e32 v127, v108, v32
	v_fmac_f32_e32 v127, v110, v34
	v_fmac_f32_e32 v127, v111, v35
	ds_read_b128 v[36:39], v60 offset:9216
	ds_read_b128 v[32:35], v60 offset:13312
	ds_read_b128 v[40:43], v60 offset:17408
	ds_read_b128 v[138:141], v60 offset:25600
	v_fmac_f32_e32 v133, v108, v134
	v_fmac_f32_e32 v133, v110, v136
	s_waitcnt lgkmcnt(3)
	v_fma_f32 v129, v109, v37, v46
	s_waitcnt lgkmcnt(2)
	v_fma_f32 v130, v109, v33, v45
	v_fmac_f32_e32 v133, v111, v137
	v_fmac_f32_e32 v129, v108, v36
	v_fmac_f32_e32 v130, v108, v32
	s_waitcnt lgkmcnt(0)
	v_fma_f32 v134, v109, v139, v52
	v_fmac_f32_e32 v129, v110, v38
	v_fmac_f32_e32 v130, v110, v34
	v_fma_f32 v132, v109, v41, v44
	v_fmac_f32_e32 v134, v108, v138
	v_fmac_f32_e32 v129, v111, v39
	v_fmac_f32_e32 v130, v111, v35
	v_fmac_f32_e32 v132, v108, v40
	v_fmac_f32_e32 v134, v110, v140
	v_fmac_f32_e32 v132, v110, v42
	v_fmac_f32_e32 v134, v111, v141
	v_fmac_f32_e32 v132, v111, v43
	ds_read_b128 v[52:55], v60 offset:33792
	ds_read_b128 v[138:141], v60 offset:37888
	s_waitcnt lgkmcnt(1)
	v_fma_f32 v136, v109, v53, v50
	v_fmac_f32_e32 v136, v108, v52
	v_fmac_f32_e32 v136, v110, v54
	v_fmac_f32_e32 v136, v111, v55
	ds_read_b128 v[50:53], v60 offset:41984
	s_waitcnt lgkmcnt(1)
	v_fma_f32 v137, v109, v139, v49
	v_fmac_f32_e32 v137, v108, v138
	v_fmac_f32_e32 v137, v110, v140
	v_fmac_f32_e32 v137, v111, v141
	ds_read_b128 v[140:143], v60 offset:46080
	s_waitcnt lgkmcnt(1)
	v_fma_f32 v138, v109, v51, v48
	v_fmac_f32_e32 v138, v108, v50
	v_fmac_f32_e32 v138, v110, v52
	v_fmac_f32_e32 v138, v111, v53
	ds_read_b128 v[48:51], v234 offset:2048
	ds_read_b128 v[52:55], v234 offset:6144
	s_waitcnt lgkmcnt(2)
	v_fma_f32 v131, v109, v141, v131
	v_fmac_f32_e32 v131, v108, v140
	v_fmac_f32_e32 v131, v110, v142
	v_fmac_f32_e32 v131, v111, v143
	ds_read_b128 v[140:143], v60 offset:54272
	v_fma_f32 v139, v109, v145, v125
	v_fmac_f32_e32 v139, v108, v144
	v_fmac_f32_e32 v139, v110, v146
	v_fmac_f32_e32 v139, v111, v147
	ds_read_b128 v[144:147], v60 offset:58368
	s_waitcnt lgkmcnt(1)
	v_fma_f32 v148, v109, v141, v124
	v_fmac_f32_e32 v148, v108, v140
	v_fmac_f32_e32 v148, v110, v142
	v_fmac_f32_e32 v148, v111, v143
	ds_read_b128 v[140:143], v60 offset:62464
	s_waitcnt lgkmcnt(1)
	v_mul_f32_e32 v124, v109, v145
	v_fmac_f32_e32 v124, v108, v144
	v_fmac_f32_e32 v124, v110, v146
	v_fmac_f32_e32 v124, v111, v147
	v_add_f32_e32 v144, v122, v124
	s_waitcnt lgkmcnt(0)
	v_mul_f32_e32 v122, v109, v141
	v_fmac_f32_e32 v122, v108, v140
	v_fmac_f32_e32 v122, v110, v142
	v_fmac_f32_e32 v122, v111, v143
	v_add_f32_e32 v142, v123, v122
	v_pk_mul_f32 v[20:21], v[102:103], v[98:99] op_sel_hi:[1,0]
	v_pk_fma_f32 v[50:51], v[20:21], v[50:51], v[54:55]
	v_pk_mul_f32 v[16:17], v[100:101], v[98:99] op_sel_hi:[1,0]
	v_cvt_pk_bf16_f32 v21, v50, v51
	v_pk_fma_f32 v[48:49], v[16:17], v[48:49], v[52:53]
	ds_read_b128 v[16:19], v60 offset:2048
	v_cvt_pk_bf16_f32 v20, v48, v49
	v_fmac_f32_e32 v252, v50, v223
	v_fmac_f32_e32 v253, v50, v224
	v_fmac_f32_e32 v254, v50, v222
	v_fmac_f32_e32 v255, v50, v225
	v_fmac_f32_e32 v252, v51, v227
	v_fmac_f32_e32 v253, v51, v228
	v_fmac_f32_e32 v254, v51, v226
	v_fmac_f32_e32 v255, v51, v229
	v_fmac_f32_e32 v252, v48, v215
	v_fmac_f32_e32 v253, v48, v216
	v_fmac_f32_e32 v254, v48, v214
	v_fmac_f32_e32 v255, v48, v217
	v_fmac_f32_e32 v252, v49, v219
	v_fmac_f32_e32 v253, v49, v220
	v_fmac_f32_e32 v254, v49, v218
	v_fmac_f32_e32 v255, v49, v221
	global_store_dwordx2 v[86:87], v[20:21], off
	ds_read_b128 v[20:23], v60 offset:6144
	v_pk_mul_f32 v[46:47], v[94:95], v[98:99] op_sel_hi:[1,0]
	s_waitcnt lgkmcnt(1)
	v_fma_f32 v42, v49, v17, v126
	v_fmac_f32_e32 v42, v48, v16
	v_fmac_f32_e32 v42, v50, v18
	v_fmac_f32_e32 v42, v51, v19
	ds_read_b128 v[16:19], v60 offset:10240
	s_waitcnt lgkmcnt(1)
	v_fma_f32 v41, v49, v21, v127
	v_fmac_f32_e32 v41, v48, v20
	v_fmac_f32_e32 v41, v50, v22
	v_fmac_f32_e32 v41, v51, v23
	ds_read_b128 v[20:23], v60 offset:14336
	s_waitcnt lgkmcnt(1)
	v_fma_f32 v40, v49, v17, v129
	v_fmac_f32_e32 v40, v48, v16
	v_fmac_f32_e32 v40, v50, v18
	v_fmac_f32_e32 v40, v51, v19
	ds_read_b128 v[16:19], v60 offset:18432
	ds_read_b128 v[32:35], v234 offset:3072
	ds_read_b128 v[36:39], v234 offset:7168
	s_waitcnt lgkmcnt(3)
	v_fma_f32 v45, v49, v21, v130
	v_fmac_f32_e32 v45, v48, v20
	v_fmac_f32_e32 v45, v50, v22
	v_fmac_f32_e32 v45, v51, v23
	ds_read_b128 v[20:23], v60 offset:22528
	s_waitcnt lgkmcnt(3)
	v_fma_f32 v44, v49, v17, v132
	v_fmac_f32_e32 v44, v48, v16
	v_fmac_f32_e32 v44, v50, v18
	v_fmac_f32_e32 v44, v51, v19
	ds_read_b128 v[16:19], v60 offset:26624
	s_waitcnt lgkmcnt(1)
	v_fma_f32 v124, v49, v21, v133
	v_fmac_f32_e32 v124, v48, v20
	v_fmac_f32_e32 v124, v50, v22
	v_fmac_f32_e32 v124, v51, v23
	ds_read_b128 v[20:23], v60 offset:30720
	s_waitcnt lgkmcnt(1)
	v_fma_f32 v123, v49, v17, v134
	v_fmac_f32_e32 v123, v48, v16
	v_fmac_f32_e32 v123, v50, v18
	v_fmac_f32_e32 v123, v51, v19
	s_waitcnt lgkmcnt(0)
	v_fma_f32 v122, v49, v21, v135
	v_fmac_f32_e32 v122, v48, v20
	v_fmac_f32_e32 v122, v50, v22
	ds_read_b128 v[16:19], v60 offset:34816
	v_fmac_f32_e32 v122, v51, v23
	ds_read_b128 v[20:23], v60 offset:38912
	s_waitcnt lgkmcnt(1)
	v_fma_f32 v111, v49, v17, v136
	v_fmac_f32_e32 v111, v48, v16
	v_fmac_f32_e32 v111, v50, v18
	s_waitcnt lgkmcnt(0)
	v_fma_f32 v110, v49, v21, v137
	v_fmac_f32_e32 v110, v48, v20
	v_fmac_f32_e32 v111, v51, v19
	v_fmac_f32_e32 v110, v50, v22
	ds_read_b128 v[16:19], v60 offset:43008
	v_fmac_f32_e32 v110, v51, v23
	ds_read_b128 v[20:23], v60 offset:47104
	s_waitcnt lgkmcnt(1)
	v_fma_f32 v109, v49, v17, v138
	v_fmac_f32_e32 v109, v48, v16
	v_fmac_f32_e32 v109, v50, v18
	s_waitcnt lgkmcnt(0)
	v_fma_f32 v108, v49, v21, v131
	v_fmac_f32_e32 v108, v48, v20
	v_fmac_f32_e32 v109, v51, v19
	v_fmac_f32_e32 v108, v50, v22
	ds_read_b128 v[16:19], v60 offset:51200
	v_fmac_f32_e32 v108, v51, v23
	ds_read_b128 v[20:23], v60 offset:55296
	s_waitcnt lgkmcnt(1)
	v_fma_f32 v103, v49, v17, v139
	v_fmac_f32_e32 v103, v48, v16
	v_fmac_f32_e32 v103, v50, v18
	s_waitcnt lgkmcnt(0)
	v_fma_f32 v102, v49, v21, v148
	v_fmac_f32_e32 v102, v48, v20
	v_fmac_f32_e32 v103, v51, v19
	v_fmac_f32_e32 v102, v50, v22
	ds_read_b128 v[16:19], v60 offset:59392
	v_fmac_f32_e32 v102, v51, v23
	ds_read_b128 v[20:23], v60 offset:63488
	s_waitcnt lgkmcnt(1)
	v_fma_f32 v100, v49, v17, v144
	v_fmac_f32_e32 v100, v48, v16
	v_fmac_f32_e32 v100, v50, v18
	s_waitcnt lgkmcnt(0)
	v_fma_f32 v101, v49, v21, v142
	v_fmac_f32_e32 v101, v48, v20
	v_fmac_f32_e32 v101, v50, v22
	v_fmac_f32_e32 v100, v51, v19
	v_fmac_f32_e32 v101, v51, v23
	v_pk_fma_f32 v[52:53], v[46:47], v[32:33], v[36:37]
	v_pk_mul_f32 v[32:33], v[96:97], v[98:99] op_sel_hi:[1,0]
	ds_read_b128 v[94:97], v60 offset:3072
	v_pk_fma_f32 v[54:55], v[32:33], v[34:35], v[38:39]
	v_cvt_pk_bf16_f32 v32, v52, v53
	v_cvt_pk_bf16_f32 v33, v54, v55
	v_fmac_f32_e32 v252, v52, v231
	v_fmac_f32_e32 v253, v52, v232
	v_fmac_f32_e32 v254, v52, v230
	v_fmac_f32_e32 v255, v52, v233
	v_fmac_f32_e32 v252, v53, v239
	v_fmac_f32_e32 v253, v53, v240
	v_fmac_f32_e32 v254, v53, v238
	v_fmac_f32_e32 v255, v53, v241
	v_fmac_f32_e32 v252, v54, v243
	v_fmac_f32_e32 v253, v54, v244
	v_fmac_f32_e32 v254, v54, v242
	v_fmac_f32_e32 v255, v54, v245
	v_fmac_f32_e32 v252, v55, v247
	v_fmac_f32_e32 v253, v55, v248
	v_fmac_f32_e32 v254, v55, v246
	v_fmac_f32_e32 v255, v55, v249
	global_store_dwordx2 v[86:87], v[32:33], off offset:512
	ds_read_b128 v[32:35], v60 offset:7168
	s_waitcnt lgkmcnt(1)
	v_mul_f32_e32 v36, v53, v95
	v_fmac_f32_e32 v36, v52, v94
	v_fmac_f32_e32 v36, v54, v96
	v_fmac_f32_e32 v36, v55, v97
	v_add_f32_e32 v94, v42, v36
	ds_read_b128 v[36:39], v60 offset:11264
	ds_read_b128 v[130:133], v60 offset:15360
	s_waitcnt lgkmcnt(2)
	v_fma_f32 v95, v53, v33, v41
	v_fmac_f32_e32 v95, v52, v32
	v_fmac_f32_e32 v95, v54, v34
	s_waitcnt lgkmcnt(1)
	v_fma_f32 v96, v53, v37, v40
	v_fmac_f32_e32 v96, v52, v36
	v_fmac_f32_e32 v96, v54, v38
	v_fmac_f32_e32 v95, v55, v35
	v_fmac_f32_e32 v96, v55, v39
	ds_read_b128 v[40:43], v60 offset:19456
	s_waitcnt lgkmcnt(1)
	v_fma_f32 v97, v53, v131, v45
	v_fmac_f32_e32 v97, v52, v130
	v_fmac_f32_e32 v97, v54, v132
	v_fmac_f32_e32 v97, v55, v133
	ds_read_b128 v[130:133], v60 offset:23552
	s_waitcnt lgkmcnt(1)
	v_fma_f32 v125, v53, v41, v44
	v_fmac_f32_e32 v125, v52, v40
	v_fmac_f32_e32 v125, v54, v42
	v_fmac_f32_e32 v125, v55, v43
	ds_read_b128 v[134:137], v60 offset:27648
	s_waitcnt lgkmcnt(1)
	v_fma_f32 v124, v53, v131, v124
	v_fmac_f32_e32 v124, v52, v130
	v_fmac_f32_e32 v124, v54, v132
	v_fmac_f32_e32 v124, v55, v133
	ds_read_b128 v[130:133], v60 offset:31744
	s_waitcnt lgkmcnt(1)
	v_fma_f32 v98, v53, v135, v123
	v_fmac_f32_e32 v98, v52, v134
	v_fmac_f32_e32 v98, v54, v136
	v_fmac_f32_e32 v98, v55, v137
	ds_read_b128 v[134:137], v60 offset:35840
	s_waitcnt lgkmcnt(1)
	v_fma_f32 v122, v53, v131, v122
	v_fmac_f32_e32 v122, v52, v130
	v_fmac_f32_e32 v122, v54, v132
	v_fmac_f32_e32 v122, v55, v133
	ds_read_b128 v[130:133], v60 offset:39936
	s_waitcnt lgkmcnt(1)
	v_fma_f32 v111, v53, v135, v111
	v_fmac_f32_e32 v111, v52, v134
	v_fmac_f32_e32 v111, v54, v136
	v_fmac_f32_e32 v111, v55, v137
	ds_read_b128 v[134:137], v60 offset:44032
	s_waitcnt lgkmcnt(1)
	v_fma_f32 v110, v53, v131, v110
	v_fmac_f32_e32 v110, v52, v130
	v_fmac_f32_e32 v110, v54, v132
	v_fmac_f32_e32 v110, v55, v133
	ds_read_b128 v[130:133], v60 offset:48128
	s_waitcnt lgkmcnt(1)
	v_fma_f32 v109, v53, v135, v109
	v_fmac_f32_e32 v109, v52, v134
	v_fmac_f32_e32 v109, v54, v136
	v_fmac_f32_e32 v109, v55, v137
	ds_read_b128 v[134:137], v60 offset:52224
	s_waitcnt lgkmcnt(1)
	v_fma_f32 v108, v53, v131, v108
	v_fmac_f32_e32 v108, v52, v130
	v_fmac_f32_e32 v108, v54, v132
	v_fmac_f32_e32 v108, v55, v133
	ds_read_b128 v[130:133], v60 offset:56320
	s_waitcnt lgkmcnt(1)
	v_fma_f32 v103, v53, v135, v103
	v_fmac_f32_e32 v103, v52, v134
	v_fmac_f32_e32 v103, v54, v136
	v_fmac_f32_e32 v103, v55, v137
	ds_read_b128 v[134:137], v60 offset:60416
	s_waitcnt lgkmcnt(1)
	v_fma_f32 v102, v53, v131, v102
	v_fmac_f32_e32 v102, v52, v130
	v_fmac_f32_e32 v102, v54, v132
	v_fmac_f32_e32 v102, v55, v133
	ds_read_b128 v[130:133], v60 offset:64512
	s_waitcnt lgkmcnt(1)
	v_fma_f32 v123, v53, v135, v100
	v_fmac_f32_e32 v123, v52, v134
	v_fmac_f32_e32 v123, v54, v136
	v_fmac_f32_e32 v123, v55, v137
	s_waitcnt lgkmcnt(0)
	v_fma_f32 v129, v53, v131, v101
	v_fmac_f32_e32 v129, v52, v130
	v_fmac_f32_e32 v129, v54, v132
	v_fmac_f32_e32 v129, v55, v133
	v_add_f32_dpp v250, v252, v252 row_mirror row_mask:0xf bank_mask:0xf bound_ctrl:1
	v_add_f32_dpp v250, v253, v253 row_mirror row_mask:0xf bank_mask:0xc bound_ctrl:1
	v_add_f32_dpp v251, v254, v254 row_mirror row_mask:0xf bank_mask:0xf bound_ctrl:1
	v_add_f32_dpp v251, v255, v255 row_mirror row_mask:0xf bank_mask:0xc bound_ctrl:1
	v_add_f32_dpp v250, v250, v250 row_half_mirror row_mask:0xf bank_mask:0xf bound_ctrl:1
	s_nop 0
	v_add_f32_dpp v250, v251, v251 row_half_mirror row_mask:0xf bank_mask:0xa bound_ctrl:1
	s_nop 1
	v_add_f32_dpp v250, v250, v250 quad_perm:[1,0,3,2] row_mask:0xf bank_mask:0xf bound_ctrl:1
	s_nop 1
	v_add_f32_dpp v250, v250, v250 quad_perm:[2,3,0,1] row_mask:0xf bank_mask:0xf bound_ctrl:1
	s_nop 0
	v_readlane_b32 s2, v250, 20
	v_readlane_b32 s10, v250, 52
	v_readlane_b32 s0, v250, 4
	v_readlane_b32 s1, v250, 36
	v_mov_b32_e32 v16, s2
	v_mov_b32_e32 v17, s10
	v_readlane_b32 s2, v250, 16
	v_readlane_b32 s10, v250, 48
	v_pk_add_f32 v[16:17], s[0:1], v[16:17]
	v_readlane_b32 s0, v250, 0
	v_readlane_b32 s1, v250, 32
	v_mov_b32_e32 v18, s2
	v_mov_b32_e32 v19, s10
	v_readlane_b32 s2, v250, 24
	v_readlane_b32 s10, v250, 56
	v_pk_add_f32 v[18:19], s[0:1], v[18:19]
	v_readlane_b32 s0, v250, 8
	v_readlane_b32 s1, v250, 40
	v_mov_b32_e32 v20, s2
	v_mov_b32_e32 v21, s10
	v_pk_add_f32 v[20:21], s[0:1], v[20:21]
	v_mov_b32_e32 v25, v18
	v_add_f32_e32 v26, v20, v21
	v_mov_b32_e32 v18, v17
	v_readlane_b32 s2, v250, 28
	v_readlane_b32 s10, v250, 60
	v_readlane_b32 s0, v250, 12
	v_readlane_b32 s1, v250, 44
	v_mov_b32_e32 v20, s2
	v_mov_b32_e32 v21, s10
	v_pk_add_f32 v[20:21], s[0:1], v[20:21]
	v_add_f32_e32 v27, v20, v21
	v_mov_b32_e32 v24, v16
	v_pk_add_f32 v[16:17], v[24:25], v[18:19]
	v_mov_b32_e32 v20, v178
	v_mov_b32_e32 v21, v179
	v_mov_b32_e32 v22, v180
	v_mov_b32_e32 v23, v181
	v_add_f32_e32 v19, v26, v22
	v_pk_add_f32 v[16:17], v[16:17], v[20:21]
	v_add_f32_e32 v18, v27, v23
	v_cmp_gt_f32_e32 vcc, v17, v16
	s_nop 0
	s_nop 0
	v_cndmask_b32_e32 v20, v16, v17, vcc
	v_cmp_gt_f32_e64 s[12:13], v19, v20
	v_cndmask_b32_e64 v21, 0, 1, vcc
	s_and_b64 s[10:11], s[12:13], exec
	v_cndmask_b32_e64 v20, v20, v19, s[12:13]
	v_cmp_ngt_f32_e64 s[0:1], v18, v20
	v_readfirstlane_b32 s2, v21
	s_cselect_b32 s2, 2, s2
	s_and_b64 s[10:11], s[0:1], exec
	s_cselect_b32 s2, s2, 3
	s_cmp_eq_u32 s2, 0
	s_cbranch_scc0 .Lmy_rselb_1
	v_add_f32_dpp v94, v94, v94 row_mirror row_mask:0xf bank_mask:0xf bound_ctrl:1
	v_add_f32_dpp v94, v95, v95 row_mirror row_mask:0xf bank_mask:0xc bound_ctrl:1
	v_add_f32_dpp v96, v96, v96 row_mirror row_mask:0xf bank_mask:0xf bound_ctrl:1
	v_add_f32_dpp v96, v97, v97 row_mirror row_mask:0xf bank_mask:0xc bound_ctrl:1
	v_add_f32_dpp v94, v94, v94 row_half_mirror row_mask:0xf bank_mask:0xf bound_ctrl:1
	s_nop 0
	v_add_f32_dpp v94, v96, v96 row_half_mirror row_mask:0xf bank_mask:0xa bound_ctrl:1
	s_nop 1
	v_add_f32_dpp v94, v94, v94 quad_perm:[1,0,3,2] row_mask:0xf bank_mask:0xf bound_ctrl:1
	s_nop 1
	v_add_f32_dpp v94, v94, v94 quad_perm:[2,3,0,1] row_mask:0xf bank_mask:0xf bound_ctrl:1
	s_nop 0
	v_readlane_b32 s14, v94, 0
	v_readlane_b32 s94, v94, 16
	v_readlane_b32 s15, v94, 32
	v_readlane_b32 s95, v94, 48
	v_readlane_b32 s87, v94, 8
	v_readlane_b32 s91, v94, 24
	v_readlane_b32 s90, v94, 40
	v_readlane_b32 s92, v94, 56
	v_readlane_b32 s65, v94, 4
	v_readlane_b32 s75, v94, 20
	v_readlane_b32 s66, v94, 36
	v_readlane_b32 s78, v94, 52
	v_readlane_b32 s51, v94, 12
	v_readlane_b32 s53, v94, 28
	v_readlane_b32 s52, v94, 44
	v_readlane_b32 s54, v94, 60
	s_branch .Lmy_rselb_end
